# P7: wave 0 waits for the prefetched next-unit loads before its offset stores, other waves after the third barrier; counted waits in the image build removed (no store acks on the unit critical path)
# baseline (speedup 1.0000x reference)
.LBB0_866:
	s_or_b64 exec, exec, s[18:19]
	s_andn2_b64 vcc, exec, s[24:25]
	s_waitcnt lgkmcnt(0)
	s_barrier
	s_cbranch_vccnz .LBB0_874
	s_waitcnt vmcnt(0)
	ds_read_b32 v9, v114 offset:32768
	v_add_u32_e32 v10, -1, v126
	v_cmp_lt_i32_e32 vcc, v10, v8
	v_add_u32_e32 v11, -2, v126
	v_add_u32_e32 v12, -4, v126
	v_cndmask_b32_e32 v10, v10, v126, vcc
	v_lshlrev_b32_e32 v10, 2, v10
	s_waitcnt lgkmcnt(0)
	ds_bpermute_b32 v10, v10, v9
	v_cmp_lt_i32_e32 vcc, v11, v8
	s_mul_i32 s18, s50, 0x90
	s_mul_hi_i32 s19, s50, 0x90
	v_cndmask_b32_e32 v11, v11, v126, vcc
	s_waitcnt lgkmcnt(0)
	v_cndmask_b32_e64 v10, v10, 0, s[8:9]
	v_lshlrev_b32_e32 v11, 2, v11
	v_add_u32_e32 v10, v10, v9
	ds_bpermute_b32 v11, v11, v10
	v_cmp_lt_i32_e32 vcc, v12, v8
	s_add_u32 s18, s51, s18
	s_addc_u32 s19, s52, s19
	v_cndmask_b32_e32 v12, v12, v126, vcc
	s_waitcnt lgkmcnt(0)
	v_cndmask_b32_e64 v11, v11, 0, s[4:5]
	v_lshlrev_b32_e32 v12, 2, v12
	v_add_u32_e32 v10, v11, v10
	ds_bpermute_b32 v11, v12, v10
	v_add_u32_e32 v12, -8, v126
	v_cmp_lt_i32_e32 vcc, v12, v8
	s_waitcnt lgkmcnt(0)
	v_cndmask_b32_e64 v11, v11, 0, s[12:13]
	v_cndmask_b32_e32 v12, v12, v126, vcc
	v_lshlrev_b32_e32 v12, 2, v12
	v_add_u32_e32 v10, v11, v10
	ds_bpermute_b32 v11, v12, v10
	v_add_u32_e32 v12, -16, v126
	v_cmp_lt_i32_e32 vcc, v12, v8
	s_waitcnt lgkmcnt(0)
	v_cndmask_b32_e64 v11, v11, 0, s[6:7]
	v_cndmask_b32_e32 v12, v12, v126, vcc
	v_lshlrev_b32_e32 v12, 2, v12
	v_add_u32_e32 v10, v11, v10
	ds_bpermute_b32 v11, v12, v10
	v_subrev_u32_e32 v12, 32, v126
	v_cmp_lt_i32_e32 vcc, v12, v8
	s_waitcnt lgkmcnt(0)
	v_cndmask_b32_e64 v11, v11, 0, s[14:15]
	v_cndmask_b32_e32 v8, v12, v126, vcc
	v_lshlrev_b32_e32 v8, 2, v8
	v_add_u32_e32 v10, v11, v10
	ds_bpermute_b32 v8, v8, v10
	s_waitcnt lgkmcnt(0)
	v_cndmask_b32_e64 v8, v8, 0, s[0:1]
	v_add_u32_e32 v8, v8, v10
	v_lshlrev_b32_e32 v10, 1, v198
	ds_write_b32 v114, v8 offset:33284
	s_and_saveexec_b64 s[46:47], s[10:11]
	s_xor_b64 s[46:47], exec, s[46:47]
	s_cbranch_execz .LBB0_869
	global_store_short v10, v8, s[18:19] offset:2

.LBB0_874:
	s_waitcnt lgkmcnt(0)
	s_barrier
	s_andn2_b64 vcc, exec, s[24:25]
	s_cbranch_vccz .Lp7_w0skip
	s_waitcnt vmcnt(0)
.Lp7_w0skip:
	s_and_saveexec_b64 s[18:19], s[0:1]
	s_cbranch_execz .LBB0_854
	s_mul_i32 s46, s50, 0x600
	s_mul_hi_i32 s22, s50, 0x600
	s_add_u32 s46, s53, s46
	s_addc_u32 s47, s54, s22
	s_cmp_eq_u32 s59, 0
	s_cbranch_scc1 .LBB0_877
	v_lshl_add_u32 v5, v5, 2, 0
	ds_read_b32 v5, v5 offset:33280
	s_waitcnt lgkmcnt(0)
	v_add_u32_e32 v8, v5, v7
	v_ashrrev_i32_e32 v9, 31, v8
	v_lshl_add_u64 v[8:9], v[8:9], 1, s[46:47]
	global_store_short v[8:9], v93, off
